# nsa: first two selected-branch K/V tiles issued before the top-k ranking
# speedup vs baseline: 1.0337x; 1.0011x over previous
; #define G8_LAS __attribute__((address_space(3)))
; template <class F>
; DI void kv_pipeline(int jlo, int jhi, const u16* kb, int ldk, const u16* vb, int ldv, char* smem, int tid, F&& body) {
;   const int wid = __builtin_amdgcn_readfirstlane(tid >> 6), lane = tid & 63;
;   unsigned ksrc[2], vsrc[2];
; #pragma unroll
;   for (int i = 0; i < 2; ++i) {
;     const int row = (i * 8 + wid) * 4 + (lane >> 4), chunk = (lane & 15) ^ (row & 15);
;     ksrc[i] = (unsigned)(row * ldk + chunk * 8) * 2u;
;     const int d = (i * 8 + wid) * 8 + (lane >> 3), c16 = (lane & 7) ^ ((d >> 1) & 7);
;     vsrc[i] = (unsigned)(d * ldv + c16 * 8) * 2u;
;   }
;   G8_LAS unsigned char* lds = (G8_LAS unsigned char*)smem;
;   const unsigned ldsw = (unsigned)wid * 1024u;
;     ...
;   __syncthreads();
;   KV_ISSUE(jlo, 0);
;   if (jlo + 1 <= jhi) KV_ISSUE(jlo + 1, 1);
; DI void nsa_item(const Params& p, int b, int g, int qb, char* smem, int tid) {
;     ...
;     for (int jj = 0; jj < 8; ++jj) {
;       int n = sub + 16 * jj;
;       float x = imp[q * 132 + n];
;       bool forced = (n == 0) | (n == cur) | (n == cur - 1);
;       x = (n <= cur) ? (forced ? 1e4f : x) : -1e30f;
;       v[jj] = x; imp[q * 132 + n] = x;
;     }
;     __syncthreads();
;     int rk[8];
; #pragma unroll
;     for (int jj = 0; jj < 8; ++jj) rk[jj] = 0;
;     for (int n2 = 0; n2 <= cur; ++n2) {
.LBB0_784:
	s_lshr_b32 s2, s85, 6
	v_mul_lo_u32 v73, v89, s84
	s_add_i32 s0, s2, -1
	v_add_u32_e32 v8, s76, v73
	v_cmp_eq_u32_e32 vcc, 0, v90
	v_cmp_eq_u32_e64 s[4:5], s2, v90
	v_lshl_add_u32 v9, v90, 2, v8
	s_or_b64 s[4:5], vcc, s[4:5]
	v_cmp_eq_u32_e32 vcc, s0, v90
	v_or_b32_e32 v7, 16, v90
	v_or_b32_e32 v6, 32, v90
	v_or_b32_e32 v5, 48, v90
	v_or_b32_e32 v4, 64, v90
	v_or_b32_e32 v3, 0x50, v90
	v_or_b32_e32 v2, 0x60, v90
	v_or_b32_e32 v1, 0x70, v90
	v_lshl_add_u32 v10, v7, 2, v8
	v_lshl_add_u32 v11, v6, 2, v8
	v_lshl_add_u32 v12, v5, 2, v8
	v_lshl_add_u32 v15, v4, 2, v8
	v_lshl_add_u32 v69, v3, 2, v8
	v_lshl_add_u32 v70, v2, 2, v8
	v_lshl_add_u32 v71, v1, 2, v8
	ds_read_b32 v13, v9
	ds_read_b32 v14, v10
	ds_read_b32 v16, v11
	ds_read_b32 v66, v12
	ds_read_b32 v67, v15
	ds_read_b32 v68, v69
	ds_read_b32 v72, v70
	ds_read_b32 v74, v71
	s_or_b64 vcc, vcc, s[4:5]
	s_waitcnt lgkmcnt(7)
	v_cndmask_b32_e32 v13, v13, v232, vcc
	v_cmp_ge_u32_e32 vcc, s2, v90
	v_cmp_eq_u32_e64 s[4:5], s0, v7
	v_mov_b32_e32 v0, 0
	v_cndmask_b32_e32 v13, v231, v13, vcc
	v_cmp_eq_u32_e32 vcc, s2, v7
	s_or_b64 vcc, s[4:5], vcc
	ds_write_b32 v9, v13
	s_waitcnt lgkmcnt(7)
	v_cndmask_b32_e32 v9, v14, v232, vcc
	v_cmp_ge_u32_e32 vcc, s2, v7
	v_cmp_eq_u32_e64 s[4:5], s0, v6
	s_nop 0
	v_cndmask_b32_e32 v14, v231, v9, vcc
	v_cmp_eq_u32_e32 vcc, s2, v6
	s_or_b64 vcc, s[4:5], vcc
	v_cmp_eq_u32_e64 s[4:5], s0, v5
	s_waitcnt lgkmcnt(6)
	v_cndmask_b32_e32 v9, v16, v232, vcc
	v_cmp_ge_u32_e32 vcc, s2, v6
	ds_write_b32 v10, v14
	v_mov_b32_e32 v10, 0
	v_cndmask_b32_e32 v16, v231, v9, vcc
	v_cmp_eq_u32_e32 vcc, s2, v5
	s_or_b64 vcc, s[4:5], vcc
	v_cmp_eq_u32_e64 s[4:5], s0, v4
	s_waitcnt lgkmcnt(6)
	v_cndmask_b32_e32 v9, v66, v232, vcc
	v_cmp_ge_u32_e32 vcc, s2, v5
	ds_write_b32 v11, v16
	v_mov_b32_e32 v11, 0
	v_cndmask_b32_e32 v66, v231, v9, vcc
	v_cmp_eq_u32_e32 vcc, s2, v4
	s_or_b64 vcc, s[4:5], vcc
	v_cmp_eq_u32_e64 s[4:5], s0, v3
	s_waitcnt lgkmcnt(6)
	v_cndmask_b32_e32 v9, v67, v232, vcc
	v_cmp_ge_u32_e32 vcc, s2, v4
	ds_write_b32 v12, v66
	v_mov_b32_e32 v12, 0
	v_cndmask_b32_e32 v67, v231, v9, vcc
	v_cmp_eq_u32_e32 vcc, s2, v3
	s_or_b64 vcc, s[4:5], vcc
	v_cmp_eq_u32_e64 s[4:5], s0, v2
	s_waitcnt lgkmcnt(6)
	v_cndmask_b32_e32 v9, v68, v232, vcc
	v_cmp_ge_u32_e32 vcc, s2, v3
	ds_write_b32 v15, v67
	v_mov_b32_e32 v15, 0
	v_cndmask_b32_e32 v68, v231, v9, vcc
	v_cmp_eq_u32_e32 vcc, s2, v2
	s_or_b64 vcc, s[4:5], vcc
	ds_write_b32 v69, v68
	s_waitcnt lgkmcnt(7)
	v_cndmask_b32_e32 v9, v72, v232, vcc
	v_cmp_ge_u32_e32 vcc, s2, v2
	v_cmp_eq_u32_e64 s[4:5], s0, v1
	s_mov_b32 s0, 0
	v_cndmask_b32_e32 v69, v231, v9, vcc
	v_cmp_eq_u32_e32 vcc, s2, v1
	s_or_b64 vcc, s[4:5], vcc
	ds_write_b32 v70, v69
	s_waitcnt lgkmcnt(7)
	v_cndmask_b32_e32 v9, v74, v232, vcc
	v_cmp_ge_u32_e32 vcc, s2, v1
	s_cmp_gt_u32 s85, 63
	s_cselect_b64 s[8:9], -1, 0
	v_cndmask_b32_e32 v70, v231, v9, vcc
	ds_write_b32 v71, v70
	s_cmp_lt_u32 s85, 64
	v_mov_b32_e32 v9, 0
	v_mov_b32_e32 v71, 0
	v_mov_b32_e32 v72, 0
	s_waitcnt lgkmcnt(0)
	s_barrier
	v_readfirstlane_b32 s0, v199
	s_lshl_b32 s4, s23, 22
	s_add_u32 s4, s64, s4
	s_addc_u32 s5, s65, 0
	s_lshl_b32 s6, s22, 8
	s_add_u32 s42, s4, s6
	s_addc_u32 s43, s5, 0
	s_lshl_b32 s4, s24, 21
	s_add_u32 s44, s66, s4
	s_addc_u32 s45, s67, 0
	s_ashr_i32 s0, s0, 6
	s_lshl_b32 s4, s0, 2
	v_or_b32_e32 v148, s4, v168
	v_bitop3_b32 v149, s4, v199, v168 bitop3:0x36
	v_lshlrev_b32_e32 v148, 9, v148
	v_lshlrev_b32_e32 v149, 4, v149
	v_and_or_b32 v150, v149, s79, v148
	v_lshl_or_b32 v148, s0, 3, v169
	v_lshrrev_b32_e32 v149, 1, v148
	v_xor_b32_e32 v149, v149, v199
	v_lshlrev_b32_e32 v148, 14, v148
	v_lshlrev_b32_e32 v149, 4, v149
	v_and_or_b32 v151, v149, s80, v148
	s_add_i32 s4, s0, 8
	s_lshl_b32 s5, s4, 2
	v_or_b32_e32 v148, s5, v168
	v_bitop3_b32 v149, s5, v199, v168 bitop3:0x36
	v_lshlrev_b32_e32 v148, 9, v148
	v_lshlrev_b32_e32 v149, 4, v149
	v_and_or_b32 v152, v149, s79, v148
	v_lshl_or_b32 v148, s4, 3, v169
	v_lshrrev_b32_e32 v149, 1, v148
	v_xor_b32_e32 v149, v149, v199
	v_lshlrev_b32_e32 v148, 14, v148
	v_lshlrev_b32_e32 v149, 4, v149
	v_and_or_b32 v153, v149, s80, v148
	s_lshl_b32 s54, s0, 10
	s_mov_b32 m0, s54
	s_add_i32 s0, s54, 0x4000
	global_load_lds_dwordx4 v150, s[42:43]
	s_mov_b32 m0, s0
	s_add_i32 s0, s54, 0x2000
	global_load_lds_dwordx4 v151, s[44:45]
	s_mov_b32 m0, s0
	s_add_i32 s0, s54, 0x6000
	global_load_lds_dwordx4 v152, s[42:43]
	s_mov_b32 m0, s0
	s_and_b64 vcc, exec, s[8:9]
	global_load_lds_dwordx4 v153, s[44:45]
	s_cbranch_vccz .Lsel_pre_done
	s_add_u32 s4, s42, 0x8000
	s_addc_u32 s5, s43, 0
	s_add_u32 s6, s44, 0x80
	s_addc_u32 s7, s45, 0
	s_add_i32 m0, s54, 0x8000
	s_add_i32 s0, s54, 0xc000
	global_load_lds_dwordx4 v150, s[4:5]
	s_mov_b32 m0, s0
	s_add_i32 s0, s54, 0xa000
	global_load_lds_dwordx4 v151, s[6:7]
	s_mov_b32 m0, s0
	s_add_i32 s0, s54, 0xe000
	global_load_lds_dwordx4 v152, s[4:5]
	s_mov_b32 m0, s0
	s_nop 0
	global_load_lds_dwordx4 v153, s[6:7]
.Lsel_pre_done:
	s_cmp_lt_u32 s85, 64
	s_cbranch_scc1 .LBB0_788
	v_writelane_b32 v255, s8, 28
	s_add_i32 s0, s2, 1
	s_and_b32 s3, s0, 0x7fffffe
	v_writelane_b32 v255, s9, 29
	v_writelane_b32 v255, s25, 30
	v_writelane_b32 v255, s24, 31
	v_writelane_b32 v255, s23, 32
	v_writelane_b32 v255, s22, 33
	v_writelane_b32 v255, s85, 34
	v_mov_b32_e32 v72, 0
	v_readlane_b32 s0, v255, 8
	v_mov_b32_e32 v71, 0
	v_mov_b32_e32 v15, 0
	v_add_u32_e32 v73, s0, v73
	s_mov_b32 s0, 0
	v_mov_b32_e32 v12, 0
	v_mov_b32_e32 v11, 0
	v_mov_b32_e32 v10, 0
	v_mov_b32_e32 v9, 0
	v_mov_b32_e32 v0, 0
	v_sub_u32_e32 v132, 0xff, v90
	v_mov_b32_e32 v133, v13
	v_sub_u32_e32 v134, 0xff, v7
	v_mov_b32_e32 v135, v14
	v_sub_u32_e32 v136, 0xff, v6
	v_mov_b32_e32 v137, v16
	v_sub_u32_e32 v138, 0xff, v5
	v_mov_b32_e32 v139, v66
	v_sub_u32_e32 v140, 0xff, v4
	v_mov_b32_e32 v141, v67
	v_sub_u32_e32 v142, 0xff, v3
	v_mov_b32_e32 v143, v68
	v_sub_u32_e32 v144, 0xff, v2
	v_mov_b32_e32 v145, v69
	v_sub_u32_e32 v146, 0xff, v1
	v_mov_b32_e32 v147, v70

; #define G8_LAS __attribute__((address_space(3)))
; template <class F>
; DI void kv_pipeline(int jlo, int jhi, const u16* kb, int ldk, const u16* vb, int ldv, char* smem, int tid, F&& body) {
;   const int wid = __builtin_amdgcn_readfirstlane(tid >> 6), lane = tid & 63;
;   unsigned ksrc[2], vsrc[2];
; #pragma unroll
;   for (int i = 0; i < 2; ++i) {
;     const int row = (i * 8 + wid) * 4 + (lane >> 4), chunk = (lane & 15) ^ (row & 15);
;     ksrc[i] = (unsigned)(row * ldk + chunk * 8) * 2u;
;     const int d = (i * 8 + wid) * 8 + (lane >> 3), c16 = (lane & 7) ^ ((d >> 1) & 7);
;     vsrc[i] = (unsigned)(d * ldv + c16 * 8) * 2u;
;   }
;   G8_LAS unsigned char* lds = (G8_LAS unsigned char*)smem;
;   const unsigned ldsw = (unsigned)wid * 1024u;
;     ...
;   __syncthreads();
;   KV_ISSUE(jlo, 0);
;   if (jlo + 1 <= jhi) KV_ISSUE(jlo + 1, 1);
; DI void nsa_item(const Params& p, int b, int g, int qb, char* smem, int tid) {
;     ...
; #pragma unroll
;     for (int jj = 0; jj < 8; ++jj) {
;       int n = sub + 16 * jj;
;       if (n <= cur && rk[jj] < 16) atomicOr(&sel[q * 4 + (n >> 5)], 1u << (n & 31));
;     }
;   }
;   {
;     float mx2 = -1e30f, l2 = 0.f;
;     const u16* kb = p.Ks + (size_t)b * SQ * 256 + g * 128;
;     const u16* vb = p.VsT + (size_t)bg * 128 * SQ;
;     kv_pipeline(0, cur, kb, 256, vb, SQ, smem, tid, [&](int j, const char* Kb, const char* Vb) __attribute__((always_inline)) {
.LBB0_790:
	v_lshlrev_b32_e32 v8, 2, v89
	v_cmp_ge_u32_e32 vcc, s2, v90
	v_cmp_gt_i32_e64 s[4:5], 16, v72
	s_and_b64 s[6:7], vcc, s[4:5]
	v_lshlrev_b32_e64 v13, v90, 1
	v_lshl_add_u32 v14, v8, 2, 0
	s_and_saveexec_b64 s[4:5], s[6:7]
	v_add_u32_e32 v16, 0x24200, v14
	ds_or_b32 v16, v13
	s_or_b64 exec, exec, s[4:5]
	v_cmp_ge_u32_e32 vcc, s2, v7
	v_cmp_gt_i32_e64 s[4:5], 16, v71
	s_and_b64 s[6:7], vcc, s[4:5]
	v_lshlrev_b32_e64 v7, v90, s81
	s_and_saveexec_b64 s[4:5], s[6:7]
	v_add_u32_e32 v14, 0x24200, v14
	ds_or_b32 v14, v7
	s_or_b64 exec, exec, s[4:5]
	v_cmp_ge_u32_e32 vcc, s2, v6
	v_cmp_gt_i32_e64 s[4:5], 16, v15
	s_and_b64 s[6:7], vcc, s[4:5]
	s_and_saveexec_b64 s[4:5], s[6:7]
	s_add_i32 s0, 0, 0x24200
	v_lshl_add_u32 v6, v8, 2, s0
	ds_or_b32 v6, v13 offset:4
	s_or_b64 exec, exec, s[4:5]
	v_cmp_ge_u32_e32 vcc, s2, v5
	v_cmp_gt_i32_e64 s[4:5], 16, v12
	s_and_b64 s[6:7], vcc, s[4:5]
	s_and_saveexec_b64 s[4:5], s[6:7]
	s_add_i32 s0, 0, 0x24200
	v_lshl_add_u32 v5, v8, 2, s0
	ds_or_b32 v5, v7 offset:4
	s_or_b64 exec, exec, s[4:5]
	v_cmp_ge_u32_e32 vcc, s2, v4
	v_cmp_gt_i32_e64 s[4:5], 16, v11
	s_and_b64 s[6:7], vcc, s[4:5]
	s_and_saveexec_b64 s[4:5], s[6:7]
	s_add_i32 s0, 0, 0x24200
	v_lshl_add_u32 v4, v8, 2, s0
	ds_or_b32 v4, v13 offset:8
	s_or_b64 exec, exec, s[4:5]
	v_cmp_ge_u32_e32 vcc, s2, v3
	v_cmp_gt_i32_e64 s[4:5], 16, v10
	s_and_b64 s[6:7], vcc, s[4:5]
	s_and_saveexec_b64 s[4:5], s[6:7]
	s_add_i32 s0, 0, 0x24200
	v_lshl_add_u32 v3, v8, 2, s0
	ds_or_b32 v3, v7 offset:8
	s_or_b64 exec, exec, s[4:5]
	v_cmp_ge_u32_e32 vcc, s2, v2
	v_cmp_gt_i32_e64 s[4:5], 16, v9
	s_and_b64 s[6:7], vcc, s[4:5]
	s_and_saveexec_b64 s[4:5], s[6:7]
	s_add_i32 s0, 0, 0x24200
	v_lshl_add_u32 v2, v8, 2, s0
	ds_or_b32 v2, v13 offset:12
	s_or_b64 exec, exec, s[4:5]
	v_cmp_ge_u32_e32 vcc, s2, v1
	v_cmp_gt_i32_e64 s[4:5], 16, v0
	s_and_b64 s[6:7], vcc, s[4:5]
	s_and_saveexec_b64 s[4:5], s[6:7]
	s_add_i32 s0, 0, 0x24200
	v_lshl_add_u32 v0, v8, 2, s0
	ds_or_b32 v0, v7 offset:12
	s_or_b64 exec, exec, s[4:5]
	s_lshl_b32 s3, s23, 21
	s_lshl_b32 s0, s23, 22
	s_add_u32 s0, s64, s0
	s_addc_u32 s4, s65, 0
	s_lshl_b32 s52, s22, 7
	s_lshl_b32 s5, s22, 8
	s_add_u32 s42, s0, s5
	s_addc_u32 s43, s4, 0
	s_lshl_b32 s53, s24, 20
	s_lshl_b32 s0, s24, 21
	s_add_u32 s44, s66, s0
	v_readfirstlane_b32 s0, v199
	s_addc_u32 s45, s67, 0
	s_ashr_i32 s0, s0, 6
	s_lshl_b32 s4, s0, 2
	v_or_b32_e32 v0, s4, v168
	v_bitop3_b32 v1, s4, v199, v168 bitop3:0x36
	v_lshlrev_b32_e32 v0, 9, v0
	v_lshlrev_b32_e32 v1, 4, v1
	v_and_or_b32 v16, v1, s79, v0
	v_lshl_or_b32 v0, s0, 3, v169
	v_lshrrev_b32_e32 v1, 1, v0
	v_xor_b32_e32 v1, v1, v199
	s_add_i32 s4, s0, 8
	v_lshlrev_b32_e32 v0, 14, v0
	v_lshlrev_b32_e32 v1, 4, v1
	s_lshl_b32 s5, s4, 2
	v_and_or_b32 v162, v1, s80, v0
	v_or_b32_e32 v0, s5, v168
	v_bitop3_b32 v1, s5, v199, v168 bitop3:0x36
	v_lshlrev_b32_e32 v0, 9, v0
	v_lshlrev_b32_e32 v1, 4, v1
	s_lshl_b32 s0, s0, 10
	v_and_or_b32 v164, v1, s79, v0
	v_lshl_or_b32 v0, s4, 3, v169
	s_add_i32 s54, s0, 0
	v_lshrrev_b32_e32 v1, 1, v0
	s_add_i32 s0, s54, 0x4000
	s_mov_b32 m0, s54
	v_xor_b32_e32 v1, v1, v199
	s_waitcnt lgkmcnt(0)
	s_barrier
	s_mov_b32 m0, s0
	v_lshlrev_b32_e32 v0, 14, v0
	v_lshlrev_b32_e32 v1, 4, v1
	s_add_i32 m0, s54, 0x2000
	v_and_or_b32 v166, v1, s80, v0
	s_add_i32 m0, s54, 0x6000
	v_mov_b32_e32 v163, v17
	v_mov_b32_e32 v165, v17
	v_mov_b32_e32 v167, v17
	s_and_b64 vcc, exec, s[8:9]
	s_cbranch_vccz .LBB0_808
	s_add_u32 s4, s42, 0x8000
	s_addc_u32 s5, s43, 0
	v_lshl_add_u64 v[0:1], s[44:45], 0, v[162:163]
	v_lshl_add_u64 v[4:5], s[4:5], 0, v[16:17]
	v_lshl_add_u64 v[6:7], s[4:5], 0, v[164:165]
	s_add_i32 m0, s54, 0x8000
	s_add_i32 s4, s54, 0xc000
	v_lshl_add_u64 v[0:1], v[0:1], 0, s[82:83]
	s_add_i32 s0, s54, 0xa000
	s_mov_b32 m0, s4
	v_lshl_add_u64 v[2:3], s[44:45], 0, v[166:167]
	s_add_i32 s5, s54, 0xe000
	s_mov_b32 m0, s0
	v_lshl_add_u64 v[2:3], v[2:3], 0, s[82:83]
	s_mov_b32 m0, s5
	s_nop 0
